# layer-1 bias vectors off the critical path: w_in part in the idle tail of the layer-0 w_out phase, gate/up part on the 40 workgroups without a last-round unit in the layer-0 gate/up GEMM
# baseline (speedup 1.0000x reference)
.LBB0_741:
	s_mov_b64 s[98:99], s[8:9]
	s_mov_b32 s0, 0
	s_cmp_eq_u32 s70, 0x100
	s_cselect_b32 s94, 0xd8, 0
	s_lshl_b32 s95, s94, 3
	s_sub_i32 s95, s90, s95
	s_sub_i32 s96, s70, s94
	s_load_dwordx2 s[8:9], s[82:83], 0xb0
	s_cmp_lt_i32 s93, s94
	s_cbranch_scc1 .Lb2_done
	v_mbcnt_lo_u32_b32 v0, -1, s0
	v_mbcnt_hi_u32_b32 v130, -1, v0
	s_lshl_b32 s10, s95, 2
	v_lshlrev_b32_e32 v64, 4, v130
	v_lshlrev_b32_e32 v131, 2, v130
	v_cmp_eq_u32_e64 s[6:7], 0, v130
.LBB0_917:
	s_cmpk_gt_i32 s95, 0x57f
	s_cbranch_scc1 .Lb2_done
	v_ashrrev_i32_e32 v65, 31, v64
	s_waitcnt lgkmcnt(0)
	v_lshl_add_u64 v[0:1], v[64:65], 2, s[8:9]
	s_mov_b64 s[0:1], 0x31000
	v_lshl_add_u64 v[66:67], v[0:1], 0, s[0:1]
	s_mov_b64 s[0:1], 0x37000
	v_lshl_add_u64 v[68:69], v[0:1], 0, s[0:1]
	s_mov_b64 s[0:1], 0x3d000
	v_lshl_add_u64 v[70:71], v[0:1], 0, s[0:1]
	s_mov_b64 s[0:1], 0x43000
	s_lshl_b32 s4, s96, 5
	v_lshl_add_u64 v[72:73], v[0:1], 0, s[0:1]
	s_mov_b64 s[0:1], 0x49000
	s_ashr_i32 s11, s10, 31
	v_lshl_add_u64 v[74:75], v[0:1], 0, s[0:1]
	s_lshl_b64 s[0:1], s[10:11], 11
	s_ashr_i32 s5, s4, 31
	v_xor_b32_e32 v128, 0x80, v131
	v_cmp_eq_u32_e64 s[6:7], 0, v130
	v_lshl_add_u64 v[64:65], v[64:65], 1, s[0:1]
	s_lshl_b64 s[12:13], s[4:5], 11
	s_lshl_b64 s[14:15], s[10:11], 2
	s_lshl_b64 s[16:17], s[4:5], 2
	s_mov_b64 s[18:19], 0x1f00000
	s_mov_b64 s[20:21], 0x1f00800
	s_mov_b64 s[22:23], 0x1f01000
	s_mov_b32 s0, 0x1f01000
	s_mov_b64 s[24:25], 0x1f01800
	v_mov_b32_e32 v129, 0xda000
	v_mov_b32_e32 v130, 0xe0000
	v_mov_b32_e32 v131, 0xe5000
	v_mov_b32_e32 v132, 0xeb000
	v_mov_b32_e32 v133, 0xf0000
	s_branch .LBB0_920

.Lb2_done:
	s_waitcnt lgkmcnt(0)
	s_mov_b64 s[8:9], s[98:99]
	s_and_b64 vcc, exec, s[76:77]
	s_mov_b64 s[10:11], 0
	s_cbranch_vccnz .LBB0_743
	v_mbcnt_lo_u32_b32 v0, -1, s36
	v_mbcnt_hi_u32_b32 v0, -1, v0
	v_cmp_eq_u32_e32 vcc, 0, v0
	s_and_b64 s[10:11], vcc, exec
